# R3 k/v stage: P.V transposed-fragment reads hand-scheduled five fragments ahead with counted waits
# baseline (speedup 1.0000x reference)
.LBB0_1093:
	v_add3_u32 v244, s12, v195, v219
	v_mul_f32_e32 v59, v59, v243
	v_cvt_pk_bf16_f32 v60, v120, v121
	v_cvt_pk_bf16_f32 v61, v122, v123
	v_cvt_pk_bf16_f32 v62, v180, v181
	v_cvt_pk_bf16_f32 v63, v182, v183
	v_cvt_pk_bf16_f32 v56, v116, v117
	v_cvt_pk_bf16_f32 v57, v118, v119
	v_cvt_pk_bf16_f32 v58, v178, v179
	v_cvt_pk_bf16_f32 v59, v242, v59
	ds_read_b64_tr_b16 v[104:105], v244 offset:34816
	ds_read_b64_tr_b16 v[106:107], v244 offset:43520
	ds_read_b64_tr_b16 v[108:109], v244 offset:34848
	ds_read_b64_tr_b16 v[110:111], v244 offset:43552
	ds_read_b64_tr_b16 v[120:121], v244 offset:34880
	ds_read_b64_tr_b16 v[122:123], v244 offset:43584
	ds_read_b64_tr_b16 v[180:181], v244 offset:34912
	ds_read_b64_tr_b16 v[182:183], v244 offset:43616
	ds_read_b64_tr_b16 v[116:117], v244 offset:34944
	ds_read_b64_tr_b16 v[118:119], v244 offset:43648
	s_waitcnt lgkmcnt(8)
	v_mfma_f32_16x16x32_bf16 v[100:103], v[104:107], v[60:63], v[100:103]
	ds_read_b64_tr_b16 v[250:251], v244 offset:34976
	ds_read_b64_tr_b16 v[252:253], v244 offset:43680
	s_waitcnt lgkmcnt(8)
	v_mfma_f32_16x16x32_bf16 v[96:99], v[108:111], v[60:63], v[96:99]
	ds_read_b64_tr_b16 v[104:105], v244 offset:35008
	ds_read_b64_tr_b16 v[106:107], v244 offset:43712
	s_add_i32 s58, s58, 1
	s_waitcnt lgkmcnt(8)
	v_mfma_f32_16x16x32_bf16 v[52:55], v[120:123], v[60:63], v[52:55]
	ds_read_b64_tr_b16 v[108:109], v244 offset:35040
	ds_read_b64_tr_b16 v[110:111], v244 offset:43744
	s_waitcnt lgkmcnt(8)
	v_mfma_f32_16x16x32_bf16 v[48:51], v[180:183], v[60:63], v[48:51]
	ds_read_b64_tr_b16 v[120:121], v244 offset:35072
	ds_read_b64_tr_b16 v[122:123], v244 offset:43776
	s_sub_i32 s16, s16, 64
	s_waitcnt lgkmcnt(8)
	v_mfma_f32_16x16x32_bf16 v[92:95], v[116:119], v[60:63], v[92:95]
	ds_read_b64_tr_b16 v[180:181], v244 offset:35104
	ds_read_b64_tr_b16 v[182:183], v244 offset:43808
	s_waitcnt lgkmcnt(8)
	v_mfma_f32_16x16x32_bf16 v[88:91], v[250:253], v[60:63], v[88:91]
	ds_read_b64_tr_b16 v[116:117], v244 offset:35136
	ds_read_b64_tr_b16 v[118:119], v244 offset:43840
	s_add_u32 s52, s52, 0x20000
	s_waitcnt lgkmcnt(8)
	v_mfma_f32_16x16x32_bf16 v[84:87], v[104:107], v[60:63], v[84:87]
	ds_read_b64_tr_b16 v[250:251], v244 offset:35168
	ds_read_b64_tr_b16 v[252:253], v244 offset:43872
	s_waitcnt lgkmcnt(8)
	v_mfma_f32_16x16x32_bf16 v[80:83], v[108:111], v[60:63], v[80:83]
	ds_read_b64_tr_b16 v[104:105], v244 offset:35200
	ds_read_b64_tr_b16 v[106:107], v244 offset:43904
	s_addc_u32 s53, s53, 0
	s_waitcnt lgkmcnt(8)
	v_mfma_f32_16x16x32_bf16 v[76:79], v[120:123], v[60:63], v[76:79]
	ds_read_b64_tr_b16 v[108:109], v244 offset:35232
	ds_read_b64_tr_b16 v[110:111], v244 offset:43936
	s_waitcnt lgkmcnt(8)
	v_mfma_f32_16x16x32_bf16 v[72:75], v[180:183], v[60:63], v[72:75]
	ds_read_b64_tr_b16 v[120:121], v244 offset:35264
	ds_read_b64_tr_b16 v[122:123], v244 offset:43968
	v_add_u32_e32 v236, 64, v236
	s_waitcnt lgkmcnt(8)
	v_mfma_f32_16x16x32_bf16 v[68:71], v[116:119], v[60:63], v[68:71]
	ds_read_b64_tr_b16 v[180:181], v244 offset:35296
	ds_read_b64_tr_b16 v[182:183], v244 offset:44000
	s_waitcnt lgkmcnt(8)
	v_mfma_f32_16x16x32_bf16 v[64:67], v[250:253], v[60:63], v[64:67]
	ds_read_b64_tr_b16 v[116:117], v244 offset:52224
	ds_read_b64_tr_b16 v[118:119], v244 offset:60928
	s_cmpk_eq_i32 s16, 0xfe00
	s_waitcnt lgkmcnt(8)
	v_mfma_f32_16x16x32_bf16 v[44:47], v[104:107], v[60:63], v[44:47]
	ds_read_b64_tr_b16 v[250:251], v244 offset:52256
	ds_read_b64_tr_b16 v[252:253], v244 offset:60960
	s_waitcnt lgkmcnt(8)
	v_mfma_f32_16x16x32_bf16 v[40:43], v[108:111], v[60:63], v[40:43]
	ds_read_b64_tr_b16 v[104:105], v244 offset:52288
	ds_read_b64_tr_b16 v[106:107], v244 offset:60992
	s_waitcnt lgkmcnt(8)
	v_mfma_f32_16x16x32_bf16 v[36:39], v[120:123], v[60:63], v[36:39]
	ds_read_b64_tr_b16 v[108:109], v244 offset:52320
	ds_read_b64_tr_b16 v[110:111], v244 offset:61024
	s_waitcnt lgkmcnt(8)
	v_mfma_f32_16x16x32_bf16 v[32:35], v[180:183], v[60:63], v[32:35]
	ds_read_b64_tr_b16 v[120:121], v244 offset:52352
	ds_read_b64_tr_b16 v[122:123], v244 offset:61056
	s_waitcnt lgkmcnt(8)
	v_mfma_f32_16x16x32_bf16 v[100:103], v[116:119], v[56:59], v[100:103]
	ds_read_b64_tr_b16 v[180:181], v244 offset:52384
	ds_read_b64_tr_b16 v[182:183], v244 offset:61088
	s_waitcnt lgkmcnt(8)
	v_mfma_f32_16x16x32_bf16 v[96:99], v[250:253], v[56:59], v[96:99]
	ds_read_b64_tr_b16 v[116:117], v244 offset:52416
	ds_read_b64_tr_b16 v[118:119], v244 offset:61120
	s_waitcnt lgkmcnt(8)
	v_mfma_f32_16x16x32_bf16 v[52:55], v[104:107], v[56:59], v[52:55]
	ds_read_b64_tr_b16 v[250:251], v244 offset:52448
	ds_read_b64_tr_b16 v[252:253], v244 offset:61152
	s_waitcnt lgkmcnt(8)
	v_mfma_f32_16x16x32_bf16 v[48:51], v[108:111], v[56:59], v[48:51]
	ds_read_b64_tr_b16 v[104:105], v244 offset:52480
	ds_read_b64_tr_b16 v[106:107], v244 offset:61184
	s_waitcnt lgkmcnt(8)
	v_mfma_f32_16x16x32_bf16 v[92:95], v[120:123], v[56:59], v[92:95]
	ds_read_b64_tr_b16 v[108:109], v244 offset:52512
	ds_read_b64_tr_b16 v[110:111], v244 offset:61216
	s_waitcnt lgkmcnt(8)
	v_mfma_f32_16x16x32_bf16 v[88:91], v[180:183], v[56:59], v[88:91]
	ds_read_b64_tr_b16 v[120:121], v244 offset:52544
	ds_read_b64_tr_b16 v[122:123], v244 offset:61248
	s_waitcnt lgkmcnt(8)
	v_mfma_f32_16x16x32_bf16 v[84:87], v[116:119], v[56:59], v[84:87]
	ds_read_b64_tr_b16 v[180:181], v244 offset:52576
	ds_read_b64_tr_b16 v[182:183], v244 offset:61280
	s_waitcnt lgkmcnt(8)
	v_mfma_f32_16x16x32_bf16 v[80:83], v[250:253], v[56:59], v[80:83]
	ds_read_b64_tr_b16 v[116:117], v244 offset:52608
	ds_read_b64_tr_b16 v[118:119], v244 offset:61312
	s_waitcnt lgkmcnt(8)
	v_mfma_f32_16x16x32_bf16 v[76:79], v[104:107], v[56:59], v[76:79]
	ds_read_b64_tr_b16 v[250:251], v244 offset:52640
	ds_read_b64_tr_b16 v[252:253], v244 offset:61344
	s_waitcnt lgkmcnt(8)
	v_mfma_f32_16x16x32_bf16 v[72:75], v[108:111], v[56:59], v[72:75]
	ds_read_b64_tr_b16 v[104:105], v244 offset:52672
	ds_read_b64_tr_b16 v[106:107], v244 offset:61376
	s_waitcnt lgkmcnt(8)
	v_mfma_f32_16x16x32_bf16 v[68:71], v[120:123], v[56:59], v[68:71]
	ds_read_b64_tr_b16 v[108:109], v244 offset:52704
	ds_read_b64_tr_b16 v[110:111], v244 offset:61408
	s_waitcnt lgkmcnt(8)
	v_mfma_f32_16x16x32_bf16 v[64:67], v[180:183], v[56:59], v[64:67]
	s_waitcnt lgkmcnt(6)
	v_mfma_f32_16x16x32_bf16 v[44:47], v[116:119], v[56:59], v[44:47]
	s_waitcnt vmcnt(0)
	s_waitcnt lgkmcnt(0)
	s_barrier
	v_mfma_f32_16x16x32_bf16 v[40:43], v[250:253], v[56:59], v[40:43]
	v_mfma_f32_16x16x32_bf16 v[36:39], v[104:107], v[56:59], v[36:39]
	v_mfma_f32_16x16x32_bf16 v[32:35], v[108:111], v[56:59], v[32:35]
	s_cbranch_scc1 .LBB0_1083
